# LRU pass-2 tile loop hand-written: activations prefetched one 16-token block ahead (global loads, counted vmcnt), branch-free recurrence, 2 tokens interleaved
# speedup vs baseline: 1.0129x; 1.0129x over previous
.LBB0_682:
	v_mov_b32_e32 v72, v228
	v_readlane_b32 s4, v255, 23
	v_ashrrev_i32_e32 v68, 6, v72
	v_and_b32_e32 v71, 15, v72
	v_lshl_or_b32 v58, v68, 7, v71
	v_ashrrev_i32_e32 v59, 31, v58
	v_lshlrev_b64 v[0:1], 7, v[58:59]
	v_or_b32_e32 v8, 16, v58
	v_or_b32_e32 v18, 32, v58
	v_or_b32_e32 v26, 48, v58
	v_or_b32_e32 v34, 64, v58
	v_or_b32_e32 v42, 0x50, v58
	v_or_b32_e32 v50, 0x60, v58
	v_or_b32_e32 v58, 0x70, v58
	v_and_b32_e32 v16, 48, v72
	v_readlane_b32 s5, v255, 24
	v_ashrrev_i32_e32 v9, 31, v8
	v_ashrrev_i32_e32 v19, 31, v18
	v_ashrrev_i32_e32 v27, 31, v26
	v_ashrrev_i32_e32 v35, 31, v34
	v_ashrrev_i32_e32 v43, 31, v42
	v_ashrrev_i32_e32 v51, 31, v50
	v_ashrrev_i32_e32 v59, 31, v58
	v_lshl_add_u64 v[60:61], s[4:5], 0, v[16:17]
	v_lshlrev_b64 v[8:9], 7, v[8:9]
	v_lshlrev_b64 v[18:19], 7, v[18:19]
	v_lshlrev_b64 v[26:27], 7, v[26:27]
	v_lshlrev_b64 v[34:35], 7, v[34:35]
	v_lshlrev_b64 v[42:43], 7, v[42:43]
	v_lshlrev_b64 v[50:51], 7, v[50:51]
	v_lshlrev_b64 v[58:59], 7, v[58:59]
	v_lshl_add_u64 v[4:5], v[60:61], 0, v[0:1]
	v_lshl_add_u64 v[12:13], v[60:61], 0, v[8:9]
	v_lshl_add_u64 v[22:23], v[60:61], 0, v[18:19]
	v_lshl_add_u64 v[30:31], v[60:61], 0, v[26:27]
	v_lshl_add_u64 v[38:39], v[60:61], 0, v[34:35]
	v_lshl_add_u64 v[46:47], v[60:61], 0, v[42:43]
	v_lshl_add_u64 v[54:55], v[60:61], 0, v[50:51]
	v_lshl_add_u64 v[62:63], v[60:61], 0, v[58:59]
	flat_load_dwordx4 v[0:3], v[4:5]
	s_nop 0
	flat_load_dwordx4 v[4:7], v[4:5] offset:64
	s_nop 0
	flat_load_dwordx4 v[8:11], v[12:13]
	s_nop 0
	flat_load_dwordx4 v[12:15], v[12:13] offset:64
	s_nop 0
	flat_load_dwordx4 v[18:21], v[22:23]
	s_nop 0
	flat_load_dwordx4 v[22:25], v[22:23] offset:64
	s_nop 0
	flat_load_dwordx4 v[26:29], v[30:31]
	s_nop 0
	flat_load_dwordx4 v[30:33], v[30:31] offset:64
	s_nop 0
	flat_load_dwordx4 v[34:37], v[38:39]
	s_nop 0
	flat_load_dwordx4 v[38:41], v[38:39] offset:64
	s_nop 0
	flat_load_dwordx4 v[42:45], v[46:47]
	s_nop 0
	flat_load_dwordx4 v[46:49], v[46:47] offset:64
	s_nop 0
	flat_load_dwordx4 v[50:53], v[54:55]
	s_nop 0
	flat_load_dwordx4 v[54:57], v[54:55] offset:64
	s_nop 0
	flat_load_dwordx4 v[58:61], v[62:63]
	s_nop 0
	flat_load_dwordx4 v[62:65], v[62:63] offset:64
	s_mov_b32 s8, 0
	s_ashr_i32 s9, s8, 31
	s_lshl_b32 s4, s28, 6
	s_lshl_b64 s[8:9], s[8:9], 3
	s_add_u32 s8, s0, s8
	s_addc_u32 s9, s1, s9
	s_load_dwordx2 s[8:9], s[8:9], 0x58
	v_readlane_b32 s14, v255, 35
	v_readlane_b32 s15, v255, 36
	v_ashrrev_i32_e32 v73, 31, v72
	s_mul_i32 s2, s28, 0x118000
	s_waitcnt lgkmcnt(0)
	s_add_u32 s8, s8, s14
	s_addc_u32 s9, s9, s15
	v_lshl_add_u64 v[66:67], v[72:73], 2, s[8:9]
	v_add_co_u32_e32 v74, vcc, s68, v66
	v_readlane_b32 s14, v255, 30
	s_nop 0
	v_addc_co_u32_e32 v75, vcc, 0, v67, vcc
	global_load_dword v16, v[66:67], off
	global_load_dword v79, v[66:67], off offset:2048
	global_load_dword v80, v[74:75], off
	global_load_dword v81, v[74:75], off offset:2048
	s_mov_b32 s8, 0
	s_ashr_i32 s9, s8, 31
	s_lshl_b64 s[8:9], s[8:9], 3
	s_add_u32 s8, s0, s8
	s_addc_u32 s9, s1, s9
	s_load_dwordx2 s[8:9], s[8:9], 0x60
	v_add_u32_e32 v66, s14, v72
	v_ashrrev_i32_e32 v67, 31, v66
	v_lshlrev_b64 v[66:67], 2, v[66:67]
	s_mul_hi_i32 s5, s4, 0x4600
	s_waitcnt lgkmcnt(0)
	v_lshl_add_u64 v[74:75], s[8:9], 0, v[66:67]
	global_load_dword v82, v[74:75], off
	s_mov_b32 s8, 0
	s_ashr_i32 s9, s8, 31
	s_lshl_b64 s[8:9], s[8:9], 3
	s_add_u32 s8, s0, s8
	s_addc_u32 s9, s1, s9
	s_load_dwordx2 s[8:9], s[8:9], 0x70
	v_readlane_b32 s15, v255, 31
	s_waitcnt lgkmcnt(0)
	v_lshl_add_u64 v[74:75], s[8:9], 0, v[66:67]
	global_load_dword v83, v[74:75], off
	s_mov_b32 s8, 0
	s_ashr_i32 s9, s8, 31
	s_lshl_b64 s[8:9], s[8:9], 3
	s_add_u32 s8, s0, s8
	s_addc_u32 s9, s1, s9
	s_load_dwordx2 s[8:9], s[8:9], 0x80
	s_waitcnt lgkmcnt(0)
	v_lshl_add_u64 v[74:75], s[8:9], 0, v[66:67]
	global_load_dword v84, v[74:75], off
	s_mov_b32 s8, 0
	s_ashr_i32 s9, s8, 31
	s_lshl_b64 s[8:9], s[8:9], 3
	s_add_u32 s8, s0, s8
	s_addc_u32 s9, s1, s9
	s_load_dwordx2 s[8:9], s[8:9], 0x88
	s_waitcnt lgkmcnt(0)
	v_lshl_add_u64 v[66:67], s[8:9], 0, v[66:67]
	global_load_dword v69, v[66:67], off
	s_add_u32 s8, s94, s2
	s_addc_u32 s9, s95, s5
	v_lshl_add_u64 v[66:67], v[72:73], 1, s[8:9]
	s_add_u32 s100, s8, 0x800
	s_addc_u32 s101, s9, 0
	v_lshlrev_b32_e32 v138, 1, v228
	v_add_u32_e32 v139, 0x4600, v138
	v_add_u32_e32 v140, 0x8c00, v138
	v_add_u32_e32 v141, 0xd200, v138
	v_add_u32_e32 v142, 0x11800, v138
	v_add_u32_e32 v143, 0x15e00, v138
	v_add_u32_e32 v144, 0x1a400, v138
	v_add_u32_e32 v145, 0x1ea00, v138
	v_add_u32_e32 v146, 0x23000, v138
	v_add_u32_e32 v147, 0x27600, v138
	v_add_u32_e32 v148, 0x2bc00, v138
	v_add_u32_e32 v149, 0x30200, v138
	v_add_u32_e32 v150, 0x34800, v138
	v_add_u32_e32 v151, 0x38e00, v138
	v_add_u32_e32 v152, 0x3d400, v138
	v_add_u32_e32 v153, 0x41a00, v138
	global_load_ushort v154, v138, s[100:101]
	global_load_ushort v155, v139, s[100:101]
	global_load_ushort v156, v140, s[100:101]
	global_load_ushort v157, v141, s[100:101]
	global_load_ushort v158, v142, s[100:101]
	global_load_ushort v159, v143, s[100:101]
	global_load_ushort v160, v144, s[100:101]
	global_load_ushort v161, v145, s[100:101]
	global_load_ushort v162, v146, s[100:101]
	global_load_ushort v163, v147, s[100:101]
	global_load_ushort v164, v148, s[100:101]
	global_load_ushort v165, v149, s[100:101]
	global_load_ushort v166, v150, s[100:101]
	global_load_ushort v167, v151, s[100:101]
	global_load_ushort v168, v152, s[100:101]
	global_load_ushort v169, v153, s[100:101]
	global_load_ushort v170, v138, s[100:101] offset:1024
	global_load_ushort v171, v139, s[100:101] offset:1024
	global_load_ushort v172, v140, s[100:101] offset:1024
	global_load_ushort v173, v141, s[100:101] offset:1024
	global_load_ushort v174, v142, s[100:101] offset:1024
	global_load_ushort v175, v143, s[100:101] offset:1024
	global_load_ushort v176, v144, s[100:101] offset:1024
	global_load_ushort v177, v145, s[100:101] offset:1024
	global_load_ushort v178, v146, s[100:101] offset:1024
	global_load_ushort v179, v147, s[100:101] offset:1024
	global_load_ushort v180, v148, s[100:101] offset:1024
	global_load_ushort v181, v149, s[100:101] offset:1024
	global_load_ushort v182, v150, s[100:101] offset:1024
	global_load_ushort v183, v151, s[100:101] offset:1024
	global_load_ushort v184, v152, s[100:101] offset:1024
	global_load_ushort v185, v153, s[100:101] offset:1024
	v_add_u32_e32 v212, 0x0, v138
	v_add_u32_e32 v213, 0x1000, v138
	v_add_u32_e32 v214, 0x2000, v138
	v_add_u32_e32 v215, 0x3000, v138
	s_and_b32 s2, s4, 0x80000fc0
	s_mov_b64 s[8:9], 0x800
	s_cmp_lt_i32 s2, 1
	v_lshl_add_u64 v[66:67], v[66:67], 0, s[8:9]
	s_cbranch_scc1 .LBB0_684
	v_add_co_u32_e32 v74, vcc, 0xffff7400, v66
	s_nop 1
	v_addc_co_u32_e32 v75, vcc, -1, v67, vcc
	flat_load_ushort v70, v[74:75]
	v_add_co_u32_e32 v74, vcc, 0xffff2e00, v66
	s_waitcnt vmcnt(0) lgkmcnt(0)
	v_lshlrev_b32_e32 v91, 16, v70
	v_addc_co_u32_e32 v75, vcc, -1, v67, vcc
	flat_load_ushort v74, v[74:75]
	s_waitcnt vmcnt(0) lgkmcnt(0)
	v_lshlrev_b32_e32 v90, 16, v74
	v_add_co_u32_e32 v74, vcc, 0xffffba00, v66
	s_nop 1
	v_addc_co_u32_e32 v75, vcc, -1, v67, vcc
	flat_load_ushort v70, v[74:75]
	s_waitcnt vmcnt(0) lgkmcnt(0)
	v_lshlrev_b32_e32 v92, 16, v70
	s_branch .LBB0_685

.LBB0_685:
	s_movk_i32 s2, 0x2940
	v_mul_lo_u32 v68, v68, s2
	s_mov_b32 s2, 0xbfb8aa3b
	v_add_u32_e32 v74, 0, v68
	s_waitcnt vmcnt(0)
	v_mul_f32_e64 v68, |v69|, s2
	v_exp_f32_e32 v75, v68
	v_max_f32_e64 v68, -v69, -v69
	v_max_f32_e32 v77, 0, v68
	s_mov_b32 s2, 0x3f2aaaab
	v_add_f32_e32 v70, 1.0, v75
	v_add_f32_e32 v68, -1.0, v70
	v_sub_f32_e32 v69, v68, v70
	v_add_f32_e32 v69, 1.0, v69
	v_sub_f32_e32 v68, v75, v68
	v_add_f32_e32 v85, v68, v69
	v_frexp_mant_f32_e32 v86, v70
	v_cvt_f64_f32_e32 v[68:69], v70
	v_frexp_exp_i32_f64_e32 v68, v[68:69]
	v_cmp_gt_f32_e32 vcc, s2, v86
	s_ashr_i32 s5, s4, 31
	s_lshl_b64 s[4:5], s[4:5], 10
	v_subbrev_co_u32_e32 v86, vcc, 0, v68, vcc
	v_sub_u32_e32 v68, 0, v86
	v_ldexp_f32 v69, v70, v68
	v_add_f32_e32 v70, -1.0, v69
	v_add_f32_e32 v88, 1.0, v69
	v_ldexp_f32 v68, v85, v68
	v_add_f32_e32 v85, 1.0, v70
	v_add_f32_e32 v89, -1.0, v88
	v_sub_f32_e32 v85, v69, v85
	v_sub_f32_e32 v69, v69, v89
	v_add_f32_e32 v85, v68, v85
	v_add_f32_e32 v68, v68, v69
	v_add_f32_e32 v89, v88, v68
	v_rcp_f32_e32 v93, v89
	v_add_f32_e32 v87, v70, v85
	v_sub_f32_e32 v70, v87, v70
	v_sub_f32_e32 v69, v85, v70
	v_sub_f32_e32 v70, v89, v88
	v_mul_f32_e32 v88, v87, v93
	v_sub_f32_e32 v85, v68, v70
	v_mul_f32_e32 v68, v89, v88
	v_fma_f32 v70, v88, v89, -v68
	v_fmac_f32_e32 v70, v88, v85
	v_add_f32_e32 v94, v68, v70
	s_add_u32 s4, s13, s4
	v_sub_f32_e32 v95, v87, v94
	s_addc_u32 s5, s37, s5
	s_ashr_i32 s29, s28, 31
	v_sub_f32_e32 v87, v87, v95
	s_lshl_b64 s[8:9], s[28:29], 11
	v_sub_f32_e32 v68, v94, v68
	v_sub_f32_e32 v87, v87, v94
	s_add_u32 s8, s79, s8
	v_add_f32_e32 v69, v69, v87
	v_sub_f32_e32 v68, v68, v70
	s_addc_u32 s9, s48, s9
	v_add_f32_e32 v87, v68, v69
	v_lshl_add_u64 v[68:69], v[72:73], 2, s[8:9]
	flat_load_dword v70, v[68:69]
	v_add_f32_e32 v94, v95, v87
	v_mul_f32_e32 v96, v93, v94
	v_mul_f32_e32 v97, v89, v96
	v_fma_f32 v68, v96, v89, -v97
	v_fmac_f32_e32 v68, v96, v85
	v_add_f32_e32 v85, v97, v68
	v_sub_f32_e32 v89, v94, v85
	v_sub_f32_e32 v69, v95, v94
	v_sub_f32_e32 v94, v94, v89
	v_add_f32_e32 v69, v87, v69
	v_sub_f32_e32 v87, v85, v97
	v_sub_f32_e32 v85, v94, v85
	v_add_f32_e32 v69, v69, v85
	v_sub_f32_e32 v68, v87, v68
	v_cvt_f32_i32_e32 v86, v86
	v_add_f32_e32 v68, v68, v69
	v_add_f32_e32 v69, v88, v96
	v_add_f32_e32 v68, v89, v68
	v_sub_f32_e32 v85, v69, v88
	v_mul_f32_e32 v68, v93, v68
	v_sub_f32_e32 v85, v96, v85
	v_add_f32_e32 v68, v85, v68
	v_mul_f32_e32 v89, 0x3f317218, v86
	s_mov_b32 s2, 0x3f317218
	v_add_f32_e32 v85, v69, v68
	v_fma_f32 v93, v86, s2, -v89
	v_mul_f32_e32 v87, v85, v85
	v_fmac_f32_e32 v93, 0xb102e308, v86
	v_sub_f32_e32 v69, v85, v69
	v_fmamk_f32 v88, v87, 0x3e9b6dac, v232
	v_sub_f32_e32 v68, v68, v69
	v_add_f32_e32 v69, v89, v93
	v_fmaak_f32 v88, v87, v88, 0x3f2aaada
	v_sub_f32_e32 v86, v69, v89
	v_ldexp_f32 v89, v85, 1
	v_mul_f32_e32 v85, v85, v87
	v_mul_f32_e32 v85, v85, v88
	v_add_f32_e32 v87, v89, v85
	v_sub_f32_e32 v88, v87, v89
	v_ldexp_f32 v68, v68, 1
	v_sub_f32_e32 v85, v85, v88
	v_add_f32_e32 v68, v68, v85
	v_add_f32_e32 v85, v87, v68
	v_sub_f32_e32 v87, v85, v87
	v_sub_f32_e32 v68, v68, v87
	v_add_f32_e32 v87, v69, v85
	v_sub_f32_e32 v88, v87, v69
	v_sub_f32_e32 v89, v87, v88
	v_sub_f32_e32 v86, v93, v86
	v_sub_f32_e32 v69, v69, v89
	v_sub_f32_e32 v85, v85, v88
	v_add_f32_e32 v69, v85, v69
	v_add_f32_e32 v85, v86, v68
	v_sub_f32_e32 v88, v85, v86
	v_sub_f32_e32 v89, v85, v88
	v_add_f32_e32 v69, v85, v69
	v_sub_f32_e32 v86, v86, v89
	v_sub_f32_e32 v68, v68, v88
	v_add_f32_e32 v85, v87, v69
	v_add_f32_e32 v68, v68, v86
	v_sub_f32_e32 v86, v85, v87
	v_sub_f32_e32 v69, v69, v86
	v_add_f32_e32 v68, v68, v69
	s_mov_b32 s2, 0x7f800000
	v_add_f32_e32 v68, v85, v68
	v_cmp_neq_f32_e32 vcc, s2, v75
	s_mov_b32 s2, 0x33800000
	v_and_b32_e32 v76, 63, v72
	v_cndmask_b32_e32 v68, v236, v68, vcc
	v_cmp_ngt_f32_e32 vcc, -1.0, v75
	v_lshl_add_u32 v85, v76, 1, v74
	v_lshl_add_u32 v87, v76, 2, v74
	v_cndmask_b32_e32 v68, v237, v68, vcc
	v_cmp_neq_f32_e32 vcc, -1.0, v75
	s_nop 1
	v_cndmask_b32_e32 v68, v238, v68, vcc
	v_cmp_lt_f32_e64 vcc, |v75|, s2
	s_movk_i32 s2, 0x90
	s_nop 0
	v_cndmask_b32_e32 v68, v68, v75, vcc
	v_add_f32_e32 v75, v77, v68
	v_lshl_add_u64 v[68:69], v[72:73], 1, s[4:5]
	v_mad_u32_u24 v73, v71, s2, v74
	s_movk_i32 s2, 0x204
	v_and_b32_e32 v72, 48, v72
	v_mad_u32_u24 v71, v71, s2, v74
	v_mul_f32_e32 v86, 0xc1000000, v75
	s_mov_b64 s[98:99], s[4:5]
	s_mov_b64 s[4:5], 0
	v_add_u32_e32 v88, v73, v72
	v_add_u32_e32 v89, v71, v72
	s_branch .Llru2_loop
.Llru2_loop:
	s_waitcnt vmcnt(32)
	v_lshlrev_b32_e32 v154, 16, v154
	v_lshlrev_b32_e32 v155, 16, v155
	v_lshlrev_b32_e32 v156, 16, v156
	v_lshlrev_b32_e32 v157, 16, v157
	v_lshlrev_b32_e32 v158, 16, v158
	v_lshlrev_b32_e32 v159, 16, v159
	v_lshlrev_b32_e32 v160, 16, v160
	v_lshlrev_b32_e32 v161, 16, v161
	v_lshlrev_b32_e32 v162, 16, v162
	v_lshlrev_b32_e32 v163, 16, v163
	v_lshlrev_b32_e32 v164, 16, v164
	v_lshlrev_b32_e32 v165, 16, v165
	v_lshlrev_b32_e32 v166, 16, v166
	v_lshlrev_b32_e32 v167, 16, v167
	v_lshlrev_b32_e32 v168, 16, v168
	v_lshlrev_b32_e32 v169, 16, v169
	v_fma_f32 v186, v16, v90, v82
	v_fmac_f32_e32 v186, v79, v91
	v_fmac_f32_e32 v186, v80, v92
	v_fmac_f32_e32 v186, v81, v154
	v_cvt_pk_bf16_f32 v216, v186, v17
	ds_write_b16 v85, v216 offset:0
	v_fma_f32 v187, v16, v91, v82
	v_fmac_f32_e32 v187, v79, v92
	v_fmac_f32_e32 v187, v80, v154
	v_fmac_f32_e32 v187, v81, v155
	v_cvt_pk_bf16_f32 v221, v187, v17
	ds_write_b16 v85, v221 offset:144
	v_fma_f32 v188, v16, v92, v82
	v_fmac_f32_e32 v188, v79, v154
	v_fmac_f32_e32 v188, v80, v155
	v_fmac_f32_e32 v188, v81, v156
	v_cvt_pk_bf16_f32 v216, v188, v17
	ds_write_b16 v85, v216 offset:288
	v_fma_f32 v189, v16, v154, v82
	v_fmac_f32_e32 v189, v79, v155
	v_fmac_f32_e32 v189, v80, v156
	v_fmac_f32_e32 v189, v81, v157
	v_cvt_pk_bf16_f32 v221, v189, v17
	ds_write_b16 v85, v221 offset:432
	v_fma_f32 v190, v16, v155, v82
	v_fmac_f32_e32 v190, v79, v156
	v_fmac_f32_e32 v190, v80, v157
	v_fmac_f32_e32 v190, v81, v158
	v_cvt_pk_bf16_f32 v216, v190, v17
	ds_write_b16 v85, v216 offset:576
	v_fma_f32 v191, v16, v156, v82
	v_fmac_f32_e32 v191, v79, v157
	v_fmac_f32_e32 v191, v80, v158
	v_fmac_f32_e32 v191, v81, v159
	v_cvt_pk_bf16_f32 v221, v191, v17
	ds_write_b16 v85, v221 offset:720
	v_fma_f32 v192, v16, v157, v82
	v_fmac_f32_e32 v192, v79, v158
	v_fmac_f32_e32 v192, v80, v159
	v_fmac_f32_e32 v192, v81, v160
	v_cvt_pk_bf16_f32 v216, v192, v17
	ds_write_b16 v85, v216 offset:864
	v_fma_f32 v193, v16, v158, v82
	v_fmac_f32_e32 v193, v79, v159
	v_fmac_f32_e32 v193, v80, v160
	v_fmac_f32_e32 v193, v81, v161
	v_cvt_pk_bf16_f32 v221, v193, v17
	ds_write_b16 v85, v221 offset:1008
	v_fma_f32 v194, v16, v159, v82
	v_fmac_f32_e32 v194, v79, v160
	v_fmac_f32_e32 v194, v80, v161
	v_fmac_f32_e32 v194, v81, v162
	v_cvt_pk_bf16_f32 v216, v194, v17
	ds_write_b16 v85, v216 offset:1152
	v_fma_f32 v195, v16, v160, v82
	v_fmac_f32_e32 v195, v79, v161
	v_fmac_f32_e32 v195, v80, v162
	v_fmac_f32_e32 v195, v81, v163
	v_cvt_pk_bf16_f32 v221, v195, v17
	ds_write_b16 v85, v221 offset:1296
	v_fma_f32 v196, v16, v161, v82
	v_fmac_f32_e32 v196, v79, v162
	v_fmac_f32_e32 v196, v80, v163
	v_fmac_f32_e32 v196, v81, v164
	v_cvt_pk_bf16_f32 v216, v196, v17
	ds_write_b16 v85, v216 offset:1440
	v_fma_f32 v197, v16, v162, v82
	v_fmac_f32_e32 v197, v79, v163
	v_fmac_f32_e32 v197, v80, v164
	v_fmac_f32_e32 v197, v81, v165
	v_cvt_pk_bf16_f32 v221, v197, v17
	ds_write_b16 v85, v221 offset:1584
	v_fma_f32 v208, v16, v163, v82
	v_fmac_f32_e32 v208, v79, v164
	v_fmac_f32_e32 v208, v80, v165
	v_fmac_f32_e32 v208, v81, v166
	v_cvt_pk_bf16_f32 v216, v208, v17
	ds_write_b16 v85, v216 offset:1728
	v_fma_f32 v209, v16, v164, v82
	v_fmac_f32_e32 v209, v79, v165
	v_fmac_f32_e32 v209, v80, v166
	v_fmac_f32_e32 v209, v81, v167
	v_cvt_pk_bf16_f32 v221, v209, v17
	ds_write_b16 v85, v221 offset:1872
	v_fma_f32 v210, v16, v165, v82
	v_fmac_f32_e32 v210, v79, v166
	v_fmac_f32_e32 v210, v80, v167
	v_fmac_f32_e32 v210, v81, v168
	v_cvt_pk_bf16_f32 v216, v210, v17
	ds_write_b16 v85, v216 offset:2016
	v_fma_f32 v211, v16, v166, v82
	v_fmac_f32_e32 v211, v79, v167
	v_fmac_f32_e32 v211, v80, v168
	v_fmac_f32_e32 v211, v81, v169
	v_cvt_pk_bf16_f32 v221, v211, v17
	ds_write_b16 v85, v221 offset:2160
	v_mov_b32_e32 v90, v167
	v_mov_b32_e32 v91, v168
	v_mov_b32_e32 v92, v169
	s_add_u32 s100, s100, 0x46000
	s_addc_u32 s101, s101, 0
	global_load_ushort v154, v138, s[100:101]
	global_load_ushort v155, v139, s[100:101]
	global_load_ushort v156, v140, s[100:101]
	global_load_ushort v157, v141, s[100:101]
	global_load_ushort v158, v142, s[100:101]
	global_load_ushort v159, v143, s[100:101]
	global_load_ushort v160, v144, s[100:101]
	global_load_ushort v161, v145, s[100:101]
	global_load_ushort v162, v146, s[100:101]
	global_load_ushort v163, v147, s[100:101]
	global_load_ushort v164, v148, s[100:101]
	global_load_ushort v165, v149, s[100:101]
	global_load_ushort v166, v150, s[100:101]
	global_load_ushort v167, v151, s[100:101]
	global_load_ushort v168, v152, s[100:101]
	global_load_ushort v169, v153, s[100:101]
	s_waitcnt lgkmcnt(0)
	s_barrier
	ds_read_b128 v[72:75], v88
	ds_read_b128 v[134:137], v88 offset:64
	s_waitcnt lgkmcnt(1)
	v_mfma_f32_16x16x32_bf16 v[106:109], v[0:3], v[72:75], 0
	v_mfma_f32_16x16x32_bf16 v[110:113], v[8:11], v[72:75], 0
	v_mfma_f32_16x16x32_bf16 v[114:117], v[18:21], v[72:75], 0
	v_mfma_f32_16x16x32_bf16 v[118:121], v[26:29], v[72:75], 0
	v_mfma_f32_16x16x32_bf16 v[122:125], v[34:37], v[72:75], 0
	v_mfma_f32_16x16x32_bf16 v[126:129], v[42:45], v[72:75], 0
	v_mfma_f32_16x16x32_bf16 v[130:133], v[50:53], v[72:75], 0
	v_mfma_f32_16x16x32_bf16 v[72:75], v[58:61], v[72:75], 0
	s_waitcnt lgkmcnt(0)
	v_mfma_f32_16x16x32_bf16 v[106:109], v[4:7], v[134:137], v[106:109]
	v_mfma_f32_16x16x32_bf16 v[110:113], v[12:15], v[134:137], v[110:113]
	v_mfma_f32_16x16x32_bf16 v[114:117], v[22:25], v[134:137], v[114:117]
	v_mfma_f32_16x16x32_bf16 v[118:121], v[30:33], v[134:137], v[118:121]
	v_mfma_f32_16x16x32_bf16 v[122:125], v[38:41], v[134:137], v[122:125]
	v_mfma_f32_16x16x32_bf16 v[126:129], v[46:49], v[134:137], v[126:129]
	v_mfma_f32_16x16x32_bf16 v[130:133], v[54:57], v[134:137], v[130:133]
	v_mfma_f32_16x16x32_bf16 v[72:75], v[62:65], v[134:137], v[72:75]
	v_add_u32_e32 v134, 0x900, v89
	ds_write2_b32 v134, v106, v107 offset1:1
	v_add_u32_e32 v106, 0x908, v89
	ds_write2_b32 v106, v108, v109 offset1:1
	v_add_u32_e32 v106, 0x940, v89
	ds_write2_b32 v106, v110, v111 offset1:1
	v_add_u32_e32 v106, 0x948, v89
	ds_write2_b32 v106, v112, v113 offset1:1
	v_add_u32_e32 v106, 0x980, v89
	ds_write2_b32 v106, v114, v115 offset1:1
	v_add_u32_e32 v106, 0x988, v89
	ds_write2_b32 v106, v116, v117 offset1:1
	v_add_u32_e32 v106, 0x9c0, v89
	ds_write2_b32 v106, v118, v119 offset1:1
	v_add_u32_e32 v106, 0x9c8, v89
	ds_write2_b32 v106, v120, v121 offset1:1
	v_add_u32_e32 v106, 0xa00, v89
	ds_write2_b32 v106, v122, v123 offset1:1
	v_add_u32_e32 v106, 0xa08, v89
	ds_write2_b32 v106, v124, v125 offset1:1
	v_add_u32_e32 v106, 0xa40, v89
	ds_write2_b32 v106, v126, v127 offset1:1
	v_add_u32_e32 v106, 0xa48, v89
	ds_write2_b32 v106, v128, v129 offset1:1
	v_add_u32_e32 v106, 0xa80, v89
	ds_write2_b32 v106, v130, v131 offset1:1
	v_add_u32_e32 v106, 0xa88, v89
	ds_write2_b32 v106, v132, v133 offset1:1
	v_add_u32_e32 v106, 0xac0, v89
	ds_write2_b32 v106, v72, v73 offset1:1
	v_add_u32_e32 v72, 0xac8, v89
	ds_write2_b32 v72, v74, v75 offset1:1
	s_waitcnt lgkmcnt(0)
	s_barrier
	s_waitcnt vmcnt(16)
	ds_read_b32 v106, v87 offset:2304
	ds_read_b32 v107, v87 offset:2560
	ds_read_b32 v108, v87 offset:2820
	ds_read_b32 v109, v87 offset:3076
	ds_read_b32 v110, v87 offset:3336
	ds_read_b32 v111, v87 offset:3592
	ds_read_b32 v112, v87 offset:3852
	ds_read_b32 v113, v87 offset:4108
	s_waitcnt lgkmcnt(4)
	v_add_f32_e32 v216, v83, v106
	v_add_f32_e32 v221, v83, v108
	v_mul_f32_e32 v216, 0xbfb8aa3b, v216
	v_mul_f32_e32 v221, 0xbfb8aa3b, v221
	v_exp_f32_e32 v216, v216
	v_exp_f32_e32 v221, v221
	v_add_f32_e32 v220, v84, v107
	v_add_f32_e32 v225, v84, v109
	v_add_f32_e32 v216, 1.0, v216
	v_add_f32_e32 v221, 1.0, v221
	v_rcp_f32_e32 v216, v216
	v_rcp_f32_e32 v221, v221
	v_mul_f32_e32 v220, 0xbfb8aa3b, v220
	v_mul_f32_e32 v225, 0xbfb8aa3b, v225
	v_mul_f32_e32 v216, v86, v216
	v_mul_f32_e32 v221, v86, v221
	v_mul_f32_e32 v217, 0x3fb8aa3b, v216
	v_mul_f32_e32 v222, 0x3fb8aa3b, v221
	v_exp_f32_e32 v217, v217
	v_exp_f32_e32 v222, v222
	v_add_f32_e32 v216, v216, v216
	v_add_f32_e32 v221, v221, v221
	v_cmp_nlt_f32_e32 vcc, s80, v216
	v_cmp_nlt_f32_e64 s[8:9], s80, v221
	v_fmamk_f32 v219, v216, 0x3d2aaaab, v233
	v_fmamk_f32 v224, v221, 0x3d2aaaab, v233
	v_fma_f32 v218, -v217, v217, 1.0
	v_fma_f32 v223, -v222, v222, 1.0
	v_fma_f32 v219, v216, v219, 0.5
	v_fma_f32 v224, v221, v224, 0.5
	v_exp_f32_e32 v220, v220
	v_exp_f32_e32 v225, v225
	v_fma_f32 v219, v216, v219, 1.0
	v_fma_f32 v224, v221, v224, 1.0
	v_mul_f32_e64 v219, v219, -v216
	v_mul_f32_e64 v224, v224, -v221
	v_add_f32_e32 v220, 1.0, v220
	v_add_f32_e32 v225, 1.0, v225
	v_cndmask_b32_e32 v218, v219, v218, vcc
	v_cndmask_b32_e64 v223, v224, v223, s[8:9]
	v_rcp_f32_e32 v220, v220
	v_rcp_f32_e32 v225, v225
	v_sqrt_f32_e32 v218, v218
	v_sqrt_f32_e32 v223, v223
	v_lshlrev_b32_e32 v219, 16, v170
	v_lshlrev_b32_e32 v224, 16, v171
	v_mul_f32_e32 v220, v220, v218
	v_mul_f32_e32 v225, v225, v223
	v_mul_f32_e32 v216, 0x3d372713, v219
	v_mul_f32_e32 v221, 0x3d372713, v224
	v_mul_f32_e32 v218, v186, v220
	v_mul_f32_e32 v223, v187, v225
	v_mul_f32_e32 v216, v216, v219
	v_mul_f32_e32 v221, v221, v224
	v_fma_f32 v226, v70, v217, v218
	v_fma_f32 v70, v226, v222, v223
	v_fma_f32 v216, v216, v219, v219
	v_fma_f32 v221, v221, v224, v224
	v_mul_f32_e32 v216, 0xbfcc422a, v216
	v_mul_f32_e32 v221, 0xbfcc422a, v221
	v_mul_f32_e32 v216, 0x3fb8aa3b, v216
	v_mul_f32_e32 v221, 0x3fb8aa3b, v221
	v_exp_f32_e32 v216, v216
	v_exp_f32_e32 v221, v221
	v_add_f32_e32 v216, 1.0, v216
	v_add_f32_e32 v221, 1.0, v221
	v_rcp_f32_e32 v216, v216
	v_rcp_f32_e32 v221, v221
	v_mul_f32_e32 v219, v216, v219
	v_mul_f32_e32 v224, v221, v224
	v_mul_f32_e32 v219, v226, v219
	v_mul_f32_e32 v224, v70, v224
	v_cvt_pk_bf16_f32 v219, v219, v17
	v_cvt_pk_bf16_f32 v224, v224, v17
	global_store_short v212, v219, s[98:99] offset:0
	global_store_short v212, v224, s[98:99] offset:1024
	s_waitcnt lgkmcnt(0)
	ds_read_b32 v114, v87 offset:4368
	ds_read_b32 v115, v87 offset:4624
	ds_read_b32 v116, v87 offset:4884
	ds_read_b32 v117, v87 offset:5140
	ds_read_b32 v118, v87 offset:5400
	ds_read_b32 v119, v87 offset:5656
	ds_read_b32 v120, v87 offset:5916
	ds_read_b32 v121, v87 offset:6172
	v_add_f32_e32 v216, v83, v110
	v_add_f32_e32 v221, v83, v112
	v_mul_f32_e32 v216, 0xbfb8aa3b, v216
	v_mul_f32_e32 v221, 0xbfb8aa3b, v221
	v_exp_f32_e32 v216, v216
	v_exp_f32_e32 v221, v221
	v_add_f32_e32 v220, v84, v111
	v_add_f32_e32 v225, v84, v113
	v_add_f32_e32 v216, 1.0, v216
	v_add_f32_e32 v221, 1.0, v221
	v_rcp_f32_e32 v216, v216
	v_rcp_f32_e32 v221, v221
	v_mul_f32_e32 v220, 0xbfb8aa3b, v220
	v_mul_f32_e32 v225, 0xbfb8aa3b, v225
	v_mul_f32_e32 v216, v86, v216
	v_mul_f32_e32 v221, v86, v221
	v_mul_f32_e32 v217, 0x3fb8aa3b, v216
	v_mul_f32_e32 v222, 0x3fb8aa3b, v221
	v_exp_f32_e32 v217, v217
	v_exp_f32_e32 v222, v222
	v_add_f32_e32 v216, v216, v216
	v_add_f32_e32 v221, v221, v221
	v_cmp_nlt_f32_e32 vcc, s80, v216
	v_cmp_nlt_f32_e64 s[8:9], s80, v221
	v_fmamk_f32 v219, v216, 0x3d2aaaab, v233
	v_fmamk_f32 v224, v221, 0x3d2aaaab, v233
	v_fma_f32 v218, -v217, v217, 1.0
	v_fma_f32 v223, -v222, v222, 1.0
	v_fma_f32 v219, v216, v219, 0.5
	v_fma_f32 v224, v221, v224, 0.5
	v_exp_f32_e32 v220, v220
	v_exp_f32_e32 v225, v225
	v_fma_f32 v219, v216, v219, 1.0
	v_fma_f32 v224, v221, v224, 1.0
	v_mul_f32_e64 v219, v219, -v216
	v_mul_f32_e64 v224, v224, -v221
	v_add_f32_e32 v220, 1.0, v220
	v_add_f32_e32 v225, 1.0, v225
	v_cndmask_b32_e32 v218, v219, v218, vcc
	v_cndmask_b32_e64 v223, v224, v223, s[8:9]
	v_rcp_f32_e32 v220, v220
	v_rcp_f32_e32 v225, v225
	v_sqrt_f32_e32 v218, v218
	v_sqrt_f32_e32 v223, v223
	v_lshlrev_b32_e32 v219, 16, v172
	v_lshlrev_b32_e32 v224, 16, v173
	v_mul_f32_e32 v220, v220, v218
	v_mul_f32_e32 v225, v225, v223
	v_mul_f32_e32 v216, 0x3d372713, v219
	v_mul_f32_e32 v221, 0x3d372713, v224
	v_mul_f32_e32 v218, v188, v220
	v_mul_f32_e32 v223, v189, v225
	v_mul_f32_e32 v216, v216, v219
	v_mul_f32_e32 v221, v221, v224
	v_fma_f32 v226, v70, v217, v218
	v_fma_f32 v70, v226, v222, v223
	v_fma_f32 v216, v216, v219, v219
	v_fma_f32 v221, v221, v224, v224
	v_mul_f32_e32 v216, 0xbfcc422a, v216
	v_mul_f32_e32 v221, 0xbfcc422a, v221
	v_mul_f32_e32 v216, 0x3fb8aa3b, v216
	v_mul_f32_e32 v221, 0x3fb8aa3b, v221
	v_exp_f32_e32 v216, v216
	v_exp_f32_e32 v221, v221
	v_add_f32_e32 v216, 1.0, v216
	v_add_f32_e32 v221, 1.0, v221
	v_rcp_f32_e32 v216, v216
	v_rcp_f32_e32 v221, v221
	v_mul_f32_e32 v219, v216, v219
	v_mul_f32_e32 v224, v221, v224
	v_mul_f32_e32 v219, v226, v219
	v_mul_f32_e32 v224, v70, v224
	v_cvt_pk_bf16_f32 v219, v219, v17
	v_cvt_pk_bf16_f32 v224, v224, v17
	global_store_short v212, v219, s[98:99] offset:2048
	global_store_short v212, v224, s[98:99] offset:3072
	s_waitcnt lgkmcnt(4)
	v_add_f32_e32 v216, v83, v114
	v_add_f32_e32 v221, v83, v116
	v_mul_f32_e32 v216, 0xbfb8aa3b, v216
	v_mul_f32_e32 v221, 0xbfb8aa3b, v221
	v_exp_f32_e32 v216, v216
	v_exp_f32_e32 v221, v221
	v_add_f32_e32 v220, v84, v115
	v_add_f32_e32 v225, v84, v117
	v_add_f32_e32 v216, 1.0, v216
	v_add_f32_e32 v221, 1.0, v221
	v_rcp_f32_e32 v216, v216
	v_rcp_f32_e32 v221, v221
	v_mul_f32_e32 v220, 0xbfb8aa3b, v220
	v_mul_f32_e32 v225, 0xbfb8aa3b, v225
	v_mul_f32_e32 v216, v86, v216
	v_mul_f32_e32 v221, v86, v221
	v_mul_f32_e32 v217, 0x3fb8aa3b, v216
	v_mul_f32_e32 v222, 0x3fb8aa3b, v221
	v_exp_f32_e32 v217, v217
	v_exp_f32_e32 v222, v222
	v_add_f32_e32 v216, v216, v216
	v_add_f32_e32 v221, v221, v221
	v_cmp_nlt_f32_e32 vcc, s80, v216
	v_cmp_nlt_f32_e64 s[8:9], s80, v221
	v_fmamk_f32 v219, v216, 0x3d2aaaab, v233
	v_fmamk_f32 v224, v221, 0x3d2aaaab, v233
	v_fma_f32 v218, -v217, v217, 1.0
	v_fma_f32 v223, -v222, v222, 1.0
	v_fma_f32 v219, v216, v219, 0.5
	v_fma_f32 v224, v221, v224, 0.5
	v_exp_f32_e32 v220, v220
	v_exp_f32_e32 v225, v225
	v_fma_f32 v219, v216, v219, 1.0
	v_fma_f32 v224, v221, v224, 1.0
	v_mul_f32_e64 v219, v219, -v216
	v_mul_f32_e64 v224, v224, -v221
	v_add_f32_e32 v220, 1.0, v220
	v_add_f32_e32 v225, 1.0, v225
	v_cndmask_b32_e32 v218, v219, v218, vcc
	v_cndmask_b32_e64 v223, v224, v223, s[8:9]
	v_rcp_f32_e32 v220, v220
	v_rcp_f32_e32 v225, v225
	v_sqrt_f32_e32 v218, v218
	v_sqrt_f32_e32 v223, v223
	v_lshlrev_b32_e32 v219, 16, v174
	v_lshlrev_b32_e32 v224, 16, v175
	v_mul_f32_e32 v220, v220, v218
	v_mul_f32_e32 v225, v225, v223
	v_mul_f32_e32 v216, 0x3d372713, v219
	v_mul_f32_e32 v221, 0x3d372713, v224
	v_mul_f32_e32 v218, v190, v220
	v_mul_f32_e32 v223, v191, v225
	v_mul_f32_e32 v216, v216, v219
	v_mul_f32_e32 v221, v221, v224
	v_fma_f32 v226, v70, v217, v218
	v_fma_f32 v70, v226, v222, v223
	v_fma_f32 v216, v216, v219, v219
	v_fma_f32 v221, v221, v224, v224
	v_mul_f32_e32 v216, 0xbfcc422a, v216
	v_mul_f32_e32 v221, 0xbfcc422a, v221
	v_mul_f32_e32 v216, 0x3fb8aa3b, v216
	v_mul_f32_e32 v221, 0x3fb8aa3b, v221
	v_exp_f32_e32 v216, v216
	v_exp_f32_e32 v221, v221
	v_add_f32_e32 v216, 1.0, v216
	v_add_f32_e32 v221, 1.0, v221
	v_rcp_f32_e32 v216, v216
	v_rcp_f32_e32 v221, v221
	v_mul_f32_e32 v219, v216, v219
	v_mul_f32_e32 v224, v221, v224
	v_mul_f32_e32 v219, v226, v219
	v_mul_f32_e32 v224, v70, v224
	v_cvt_pk_bf16_f32 v219, v219, v17
	v_cvt_pk_bf16_f32 v224, v224, v17
	global_store_short v213, v219, s[98:99] offset:0
	global_store_short v213, v224, s[98:99] offset:1024
	s_waitcnt lgkmcnt(0)
	ds_read_b32 v106, v87 offset:6432
	ds_read_b32 v107, v87 offset:6688
	ds_read_b32 v108, v87 offset:6948
	ds_read_b32 v109, v87 offset:7204
	ds_read_b32 v110, v87 offset:7464
	ds_read_b32 v111, v87 offset:7720
	ds_read_b32 v112, v87 offset:7980
	ds_read_b32 v113, v87 offset:8236
	v_add_f32_e32 v216, v83, v118
	v_add_f32_e32 v221, v83, v120
	v_mul_f32_e32 v216, 0xbfb8aa3b, v216
	v_mul_f32_e32 v221, 0xbfb8aa3b, v221
	v_exp_f32_e32 v216, v216
	v_exp_f32_e32 v221, v221
	v_add_f32_e32 v220, v84, v119
	v_add_f32_e32 v225, v84, v121
	v_add_f32_e32 v216, 1.0, v216
	v_add_f32_e32 v221, 1.0, v221
	v_rcp_f32_e32 v216, v216
	v_rcp_f32_e32 v221, v221
	v_mul_f32_e32 v220, 0xbfb8aa3b, v220
	v_mul_f32_e32 v225, 0xbfb8aa3b, v225
	v_mul_f32_e32 v216, v86, v216
	v_mul_f32_e32 v221, v86, v221
	v_mul_f32_e32 v217, 0x3fb8aa3b, v216
	v_mul_f32_e32 v222, 0x3fb8aa3b, v221
	v_exp_f32_e32 v217, v217
	v_exp_f32_e32 v222, v222
	v_add_f32_e32 v216, v216, v216
	v_add_f32_e32 v221, v221, v221
	v_cmp_nlt_f32_e32 vcc, s80, v216
	v_cmp_nlt_f32_e64 s[8:9], s80, v221
	v_fmamk_f32 v219, v216, 0x3d2aaaab, v233
	v_fmamk_f32 v224, v221, 0x3d2aaaab, v233
	v_fma_f32 v218, -v217, v217, 1.0
	v_fma_f32 v223, -v222, v222, 1.0
	v_fma_f32 v219, v216, v219, 0.5
	v_fma_f32 v224, v221, v224, 0.5
	v_exp_f32_e32 v220, v220
	v_exp_f32_e32 v225, v225
	v_fma_f32 v219, v216, v219, 1.0
	v_fma_f32 v224, v221, v224, 1.0
	v_mul_f32_e64 v219, v219, -v216
	v_mul_f32_e64 v224, v224, -v221
	v_add_f32_e32 v220, 1.0, v220
	v_add_f32_e32 v225, 1.0, v225
	v_cndmask_b32_e32 v218, v219, v218, vcc
	v_cndmask_b32_e64 v223, v224, v223, s[8:9]
	v_rcp_f32_e32 v220, v220
	v_rcp_f32_e32 v225, v225
	v_sqrt_f32_e32 v218, v218
	v_sqrt_f32_e32 v223, v223
	v_lshlrev_b32_e32 v219, 16, v176
	v_lshlrev_b32_e32 v224, 16, v177
	v_mul_f32_e32 v220, v220, v218
	v_mul_f32_e32 v225, v225, v223
	v_mul_f32_e32 v216, 0x3d372713, v219
	v_mul_f32_e32 v221, 0x3d372713, v224
	v_mul_f32_e32 v218, v192, v220
	v_mul_f32_e32 v223, v193, v225
	v_mul_f32_e32 v216, v216, v219
	v_mul_f32_e32 v221, v221, v224
	v_fma_f32 v226, v70, v217, v218
	v_fma_f32 v70, v226, v222, v223
	v_fma_f32 v216, v216, v219, v219
	v_fma_f32 v221, v221, v224, v224
	v_mul_f32_e32 v216, 0xbfcc422a, v216
	v_mul_f32_e32 v221, 0xbfcc422a, v221
	v_mul_f32_e32 v216, 0x3fb8aa3b, v216
	v_mul_f32_e32 v221, 0x3fb8aa3b, v221
	v_exp_f32_e32 v216, v216
	v_exp_f32_e32 v221, v221
	v_add_f32_e32 v216, 1.0, v216
	v_add_f32_e32 v221, 1.0, v221
	v_rcp_f32_e32 v216, v216
	v_rcp_f32_e32 v221, v221
	v_mul_f32_e32 v219, v216, v219
	v_mul_f32_e32 v224, v221, v224
	v_mul_f32_e32 v219, v226, v219
	v_mul_f32_e32 v224, v70, v224
	v_cvt_pk_bf16_f32 v219, v219, v17
	v_cvt_pk_bf16_f32 v224, v224, v17
	global_store_short v213, v219, s[98:99] offset:2048
	global_store_short v213, v224, s[98:99] offset:3072
	s_waitcnt lgkmcnt(4)
	v_add_f32_e32 v216, v83, v106
	v_add_f32_e32 v221, v83, v108
	v_mul_f32_e32 v216, 0xbfb8aa3b, v216
	v_mul_f32_e32 v221, 0xbfb8aa3b, v221
	v_exp_f32_e32 v216, v216
	v_exp_f32_e32 v221, v221
	v_add_f32_e32 v220, v84, v107
	v_add_f32_e32 v225, v84, v109
	v_add_f32_e32 v216, 1.0, v216
	v_add_f32_e32 v221, 1.0, v221
	v_rcp_f32_e32 v216, v216
	v_rcp_f32_e32 v221, v221
	v_mul_f32_e32 v220, 0xbfb8aa3b, v220
	v_mul_f32_e32 v225, 0xbfb8aa3b, v225
	v_mul_f32_e32 v216, v86, v216
	v_mul_f32_e32 v221, v86, v221
	v_mul_f32_e32 v217, 0x3fb8aa3b, v216
	v_mul_f32_e32 v222, 0x3fb8aa3b, v221
	v_exp_f32_e32 v217, v217
	v_exp_f32_e32 v222, v222
	v_add_f32_e32 v216, v216, v216
	v_add_f32_e32 v221, v221, v221
	v_cmp_nlt_f32_e32 vcc, s80, v216
	v_cmp_nlt_f32_e64 s[8:9], s80, v221
	v_fmamk_f32 v219, v216, 0x3d2aaaab, v233
	v_fmamk_f32 v224, v221, 0x3d2aaaab, v233
	v_fma_f32 v218, -v217, v217, 1.0
	v_fma_f32 v223, -v222, v222, 1.0
	v_fma_f32 v219, v216, v219, 0.5
	v_fma_f32 v224, v221, v224, 0.5
	v_exp_f32_e32 v220, v220
	v_exp_f32_e32 v225, v225
	v_fma_f32 v219, v216, v219, 1.0
	v_fma_f32 v224, v221, v224, 1.0
	v_mul_f32_e64 v219, v219, -v216
	v_mul_f32_e64 v224, v224, -v221
	v_add_f32_e32 v220, 1.0, v220
	v_add_f32_e32 v225, 1.0, v225
	v_cndmask_b32_e32 v218, v219, v218, vcc
	v_cndmask_b32_e64 v223, v224, v223, s[8:9]
	v_rcp_f32_e32 v220, v220
	v_rcp_f32_e32 v225, v225
	v_sqrt_f32_e32 v218, v218
	v_sqrt_f32_e32 v223, v223
	v_lshlrev_b32_e32 v219, 16, v178
	v_lshlrev_b32_e32 v224, 16, v179
	v_mul_f32_e32 v220, v220, v218
	v_mul_f32_e32 v225, v225, v223
	v_mul_f32_e32 v216, 0x3d372713, v219
	v_mul_f32_e32 v221, 0x3d372713, v224
	v_mul_f32_e32 v218, v194, v220
	v_mul_f32_e32 v223, v195, v225
	v_mul_f32_e32 v216, v216, v219
	v_mul_f32_e32 v221, v221, v224
	v_fma_f32 v226, v70, v217, v218
	v_fma_f32 v70, v226, v222, v223
	v_fma_f32 v216, v216, v219, v219
	v_fma_f32 v221, v221, v224, v224
	v_mul_f32_e32 v216, 0xbfcc422a, v216
	v_mul_f32_e32 v221, 0xbfcc422a, v221
	v_mul_f32_e32 v216, 0x3fb8aa3b, v216
	v_mul_f32_e32 v221, 0x3fb8aa3b, v221
	v_exp_f32_e32 v216, v216
	v_exp_f32_e32 v221, v221
	v_add_f32_e32 v216, 1.0, v216
	v_add_f32_e32 v221, 1.0, v221
	v_rcp_f32_e32 v216, v216
	v_rcp_f32_e32 v221, v221
	v_mul_f32_e32 v219, v216, v219
	v_mul_f32_e32 v224, v221, v224
	v_mul_f32_e32 v219, v226, v219
	v_mul_f32_e32 v224, v70, v224
	v_cvt_pk_bf16_f32 v219, v219, v17
	v_cvt_pk_bf16_f32 v224, v224, v17
	global_store_short v214, v219, s[98:99] offset:0
	global_store_short v214, v224, s[98:99] offset:1024
	s_waitcnt lgkmcnt(0)
	ds_read_b32 v114, v87 offset:8496
	ds_read_b32 v115, v87 offset:8752
	ds_read_b32 v116, v87 offset:9012
	ds_read_b32 v117, v87 offset:9268
	ds_read_b32 v118, v87 offset:9528
	ds_read_b32 v119, v87 offset:9784
	ds_read_b32 v120, v87 offset:10044
	ds_read_b32 v121, v87 offset:10300
	v_add_f32_e32 v216, v83, v110
	v_add_f32_e32 v221, v83, v112
	v_mul_f32_e32 v216, 0xbfb8aa3b, v216
	v_mul_f32_e32 v221, 0xbfb8aa3b, v221
	v_exp_f32_e32 v216, v216
	v_exp_f32_e32 v221, v221
	v_add_f32_e32 v220, v84, v111
	v_add_f32_e32 v225, v84, v113
	v_add_f32_e32 v216, 1.0, v216
	v_add_f32_e32 v221, 1.0, v221
	v_rcp_f32_e32 v216, v216
	v_rcp_f32_e32 v221, v221
	v_mul_f32_e32 v220, 0xbfb8aa3b, v220
	v_mul_f32_e32 v225, 0xbfb8aa3b, v225
	v_mul_f32_e32 v216, v86, v216
	v_mul_f32_e32 v221, v86, v221
	v_mul_f32_e32 v217, 0x3fb8aa3b, v216
	v_mul_f32_e32 v222, 0x3fb8aa3b, v221
	v_exp_f32_e32 v217, v217
	v_exp_f32_e32 v222, v222
	v_add_f32_e32 v216, v216, v216
	v_add_f32_e32 v221, v221, v221
	v_cmp_nlt_f32_e32 vcc, s80, v216
	v_cmp_nlt_f32_e64 s[8:9], s80, v221
	v_fmamk_f32 v219, v216, 0x3d2aaaab, v233
	v_fmamk_f32 v224, v221, 0x3d2aaaab, v233
	v_fma_f32 v218, -v217, v217, 1.0
	v_fma_f32 v223, -v222, v222, 1.0
	v_fma_f32 v219, v216, v219, 0.5
	v_fma_f32 v224, v221, v224, 0.5
	v_exp_f32_e32 v220, v220
	v_exp_f32_e32 v225, v225
	v_fma_f32 v219, v216, v219, 1.0
	v_fma_f32 v224, v221, v224, 1.0
	v_mul_f32_e64 v219, v219, -v216
	v_mul_f32_e64 v224, v224, -v221
	v_add_f32_e32 v220, 1.0, v220
	v_add_f32_e32 v225, 1.0, v225
	v_cndmask_b32_e32 v218, v219, v218, vcc
	v_cndmask_b32_e64 v223, v224, v223, s[8:9]
	v_rcp_f32_e32 v220, v220
	v_rcp_f32_e32 v225, v225
	v_sqrt_f32_e32 v218, v218
	v_sqrt_f32_e32 v223, v223
	v_lshlrev_b32_e32 v219, 16, v180
	v_lshlrev_b32_e32 v224, 16, v181
	v_mul_f32_e32 v220, v220, v218
	v_mul_f32_e32 v225, v225, v223
	v_mul_f32_e32 v216, 0x3d372713, v219
	v_mul_f32_e32 v221, 0x3d372713, v224
	v_mul_f32_e32 v218, v196, v220
	v_mul_f32_e32 v223, v197, v225
	v_mul_f32_e32 v216, v216, v219
	v_mul_f32_e32 v221, v221, v224
	v_fma_f32 v226, v70, v217, v218
	v_fma_f32 v70, v226, v222, v223
	v_fma_f32 v216, v216, v219, v219
	v_fma_f32 v221, v221, v224, v224
	v_mul_f32_e32 v216, 0xbfcc422a, v216
	v_mul_f32_e32 v221, 0xbfcc422a, v221
	v_mul_f32_e32 v216, 0x3fb8aa3b, v216
	v_mul_f32_e32 v221, 0x3fb8aa3b, v221
	v_exp_f32_e32 v216, v216
	v_exp_f32_e32 v221, v221
	v_add_f32_e32 v216, 1.0, v216
	v_add_f32_e32 v221, 1.0, v221
	v_rcp_f32_e32 v216, v216
	v_rcp_f32_e32 v221, v221
	v_mul_f32_e32 v219, v216, v219
	v_mul_f32_e32 v224, v221, v224
	v_mul_f32_e32 v219, v226, v219
	v_mul_f32_e32 v224, v70, v224
	v_cvt_pk_bf16_f32 v219, v219, v17
	v_cvt_pk_bf16_f32 v224, v224, v17
	global_store_short v214, v219, s[98:99] offset:2048
	global_store_short v214, v224, s[98:99] offset:3072
	s_waitcnt lgkmcnt(4)
	v_add_f32_e32 v216, v83, v114
	v_add_f32_e32 v221, v83, v116
	v_mul_f32_e32 v216, 0xbfb8aa3b, v216
	v_mul_f32_e32 v221, 0xbfb8aa3b, v221
	v_exp_f32_e32 v216, v216
	v_exp_f32_e32 v221, v221
	v_add_f32_e32 v220, v84, v115
	v_add_f32_e32 v225, v84, v117
	v_add_f32_e32 v216, 1.0, v216
	v_add_f32_e32 v221, 1.0, v221
	v_rcp_f32_e32 v216, v216
	v_rcp_f32_e32 v221, v221
	v_mul_f32_e32 v220, 0xbfb8aa3b, v220
	v_mul_f32_e32 v225, 0xbfb8aa3b, v225
	v_mul_f32_e32 v216, v86, v216
	v_mul_f32_e32 v221, v86, v221
	v_mul_f32_e32 v217, 0x3fb8aa3b, v216
	v_mul_f32_e32 v222, 0x3fb8aa3b, v221
	v_exp_f32_e32 v217, v217
	v_exp_f32_e32 v222, v222
	v_add_f32_e32 v216, v216, v216
	v_add_f32_e32 v221, v221, v221
	v_cmp_nlt_f32_e32 vcc, s80, v216
	v_cmp_nlt_f32_e64 s[8:9], s80, v221
	v_fmamk_f32 v219, v216, 0x3d2aaaab, v233
	v_fmamk_f32 v224, v221, 0x3d2aaaab, v233
	v_fma_f32 v218, -v217, v217, 1.0
	v_fma_f32 v223, -v222, v222, 1.0
	v_fma_f32 v219, v216, v219, 0.5
	v_fma_f32 v224, v221, v224, 0.5
	v_exp_f32_e32 v220, v220
	v_exp_f32_e32 v225, v225
	v_fma_f32 v219, v216, v219, 1.0
	v_fma_f32 v224, v221, v224, 1.0
	v_mul_f32_e64 v219, v219, -v216
	v_mul_f32_e64 v224, v224, -v221
	v_add_f32_e32 v220, 1.0, v220
	v_add_f32_e32 v225, 1.0, v225
	v_cndmask_b32_e32 v218, v219, v218, vcc
	v_cndmask_b32_e64 v223, v224, v223, s[8:9]
	v_rcp_f32_e32 v220, v220
	v_rcp_f32_e32 v225, v225
	v_sqrt_f32_e32 v218, v218
	v_sqrt_f32_e32 v223, v223
	v_lshlrev_b32_e32 v219, 16, v182
	v_lshlrev_b32_e32 v224, 16, v183
	v_mul_f32_e32 v220, v220, v218
	v_mul_f32_e32 v225, v225, v223
	v_mul_f32_e32 v216, 0x3d372713, v219
	v_mul_f32_e32 v221, 0x3d372713, v224
	v_mul_f32_e32 v218, v208, v220
	v_mul_f32_e32 v223, v209, v225
	v_mul_f32_e32 v216, v216, v219
	v_mul_f32_e32 v221, v221, v224
	v_fma_f32 v226, v70, v217, v218
	v_fma_f32 v70, v226, v222, v223
	v_fma_f32 v216, v216, v219, v219
	v_fma_f32 v221, v221, v224, v224
	v_mul_f32_e32 v216, 0xbfcc422a, v216
	v_mul_f32_e32 v221, 0xbfcc422a, v221
	v_mul_f32_e32 v216, 0x3fb8aa3b, v216
	v_mul_f32_e32 v221, 0x3fb8aa3b, v221
	v_exp_f32_e32 v216, v216
	v_exp_f32_e32 v221, v221
	v_add_f32_e32 v216, 1.0, v216
	v_add_f32_e32 v221, 1.0, v221
	v_rcp_f32_e32 v216, v216
	v_rcp_f32_e32 v221, v221
	v_mul_f32_e32 v219, v216, v219
	v_mul_f32_e32 v224, v221, v224
	v_mul_f32_e32 v219, v226, v219
	v_mul_f32_e32 v224, v70, v224
	v_cvt_pk_bf16_f32 v219, v219, v17
	v_cvt_pk_bf16_f32 v224, v224, v17
	global_store_short v215, v219, s[98:99] offset:0
	global_store_short v215, v224, s[98:99] offset:1024
	s_waitcnt lgkmcnt(0)
	v_add_f32_e32 v216, v83, v118
	v_add_f32_e32 v221, v83, v120
	v_mul_f32_e32 v216, 0xbfb8aa3b, v216
	v_mul_f32_e32 v221, 0xbfb8aa3b, v221
	v_exp_f32_e32 v216, v216
	v_exp_f32_e32 v221, v221
	v_add_f32_e32 v220, v84, v119
	v_add_f32_e32 v225, v84, v121
	v_add_f32_e32 v216, 1.0, v216
	v_add_f32_e32 v221, 1.0, v221
	v_rcp_f32_e32 v216, v216
	v_rcp_f32_e32 v221, v221
	v_mul_f32_e32 v220, 0xbfb8aa3b, v220
	v_mul_f32_e32 v225, 0xbfb8aa3b, v225
	v_mul_f32_e32 v216, v86, v216
	v_mul_f32_e32 v221, v86, v221
	v_mul_f32_e32 v217, 0x3fb8aa3b, v216
	v_mul_f32_e32 v222, 0x3fb8aa3b, v221
	v_exp_f32_e32 v217, v217
	v_exp_f32_e32 v222, v222
	v_add_f32_e32 v216, v216, v216
	v_add_f32_e32 v221, v221, v221
	v_cmp_nlt_f32_e32 vcc, s80, v216
	v_cmp_nlt_f32_e64 s[8:9], s80, v221
	v_fmamk_f32 v219, v216, 0x3d2aaaab, v233
	v_fmamk_f32 v224, v221, 0x3d2aaaab, v233
	v_fma_f32 v218, -v217, v217, 1.0
	v_fma_f32 v223, -v222, v222, 1.0
	v_fma_f32 v219, v216, v219, 0.5
	v_fma_f32 v224, v221, v224, 0.5
	v_exp_f32_e32 v220, v220
	v_exp_f32_e32 v225, v225
	v_fma_f32 v219, v216, v219, 1.0
	v_fma_f32 v224, v221, v224, 1.0
	v_mul_f32_e64 v219, v219, -v216
	v_mul_f32_e64 v224, v224, -v221
	v_add_f32_e32 v220, 1.0, v220
	v_add_f32_e32 v225, 1.0, v225
	v_cndmask_b32_e32 v218, v219, v218, vcc
	v_cndmask_b32_e64 v223, v224, v223, s[8:9]
	v_rcp_f32_e32 v220, v220
	v_rcp_f32_e32 v225, v225
	v_sqrt_f32_e32 v218, v218
	v_sqrt_f32_e32 v223, v223
	v_lshlrev_b32_e32 v219, 16, v184
	v_lshlrev_b32_e32 v224, 16, v185
	v_mul_f32_e32 v220, v220, v218
	v_mul_f32_e32 v225, v225, v223
	v_mul_f32_e32 v216, 0x3d372713, v219
	v_mul_f32_e32 v221, 0x3d372713, v224
	v_mul_f32_e32 v218, v210, v220
	v_mul_f32_e32 v223, v211, v225
	v_mul_f32_e32 v216, v216, v219
	v_mul_f32_e32 v221, v221, v224
	v_fma_f32 v226, v70, v217, v218
	v_fma_f32 v70, v226, v222, v223
	v_fma_f32 v216, v216, v219, v219
	v_fma_f32 v221, v221, v224, v224
	v_mul_f32_e32 v216, 0xbfcc422a, v216
	v_mul_f32_e32 v221, 0xbfcc422a, v221
	v_mul_f32_e32 v216, 0x3fb8aa3b, v216
	v_mul_f32_e32 v221, 0x3fb8aa3b, v221
	v_exp_f32_e32 v216, v216
	v_exp_f32_e32 v221, v221
	v_add_f32_e32 v216, 1.0, v216
	v_add_f32_e32 v221, 1.0, v221
	v_rcp_f32_e32 v216, v216
	v_rcp_f32_e32 v221, v221
	v_mul_f32_e32 v219, v216, v219
	v_mul_f32_e32 v224, v221, v224
	v_mul_f32_e32 v219, v226, v219
	v_mul_f32_e32 v224, v70, v224
	v_cvt_pk_bf16_f32 v219, v219, v17
	v_cvt_pk_bf16_f32 v224, v224, v17
	global_store_short v215, v219, s[98:99] offset:2048
	global_store_short v215, v224, s[98:99] offset:3072
	global_load_ushort v170, v138, s[100:101] offset:1024
	global_load_ushort v171, v139, s[100:101] offset:1024
	global_load_ushort v172, v140, s[100:101] offset:1024
	global_load_ushort v173, v141, s[100:101] offset:1024
	global_load_ushort v174, v142, s[100:101] offset:1024
	global_load_ushort v175, v143, s[100:101] offset:1024
	global_load_ushort v176, v144, s[100:101] offset:1024
	global_load_ushort v177, v145, s[100:101] offset:1024
	global_load_ushort v178, v146, s[100:101] offset:1024
	global_load_ushort v179, v147, s[100:101] offset:1024
	global_load_ushort v180, v148, s[100:101] offset:1024
	global_load_ushort v181, v149, s[100:101] offset:1024
	global_load_ushort v182, v150, s[100:101] offset:1024
	global_load_ushort v183, v151, s[100:101] offset:1024
	global_load_ushort v184, v152, s[100:101] offset:1024
	global_load_ushort v185, v153, s[100:101] offset:1024
	s_add_u32 s98, s98, 0x4000
	s_addc_u32 s99, s99, 0
	s_add_u32 s4, s4, 0x4000
	s_cmp_eq_u32 s4, 0x10000
	s_barrier
	s_cbranch_scc0 .Llru2_loop
	s_branch .LBB0_572

	.amdhsa_kernel _Z14fwd_megakernel6Params
		.amdhsa_group_segment_fixed_size 0
		.amdhsa_private_segment_fixed_size 0
		.amdhsa_kernarg_size 528
		.amdhsa_user_sgpr_count 2
		.amdhsa_user_sgpr_dispatch_ptr 0
		.amdhsa_user_sgpr_queue_ptr 0
		.amdhsa_user_sgpr_kernarg_segment_ptr 1
		.amdhsa_user_sgpr_dispatch_id 0
		.amdhsa_user_sgpr_kernarg_preload_length 0
		.amdhsa_user_sgpr_kernarg_preload_offset 0
		.amdhsa_user_sgpr_private_segment_size 0
		.amdhsa_uses_dynamic_stack 0
		.amdhsa_enable_private_segment 0
		.amdhsa_system_sgpr_workgroup_id_x 1
		.amdhsa_system_sgpr_workgroup_id_y 0
		.amdhsa_system_sgpr_workgroup_id_z 0
		.amdhsa_system_sgpr_workgroup_info 0
		.amdhsa_system_vgpr_workitem_id 2
		.amdhsa_next_free_vgpr 256
		.amdhsa_next_free_sgpr 102
		.amdhsa_accum_offset 256
		.amdhsa_reserve_vcc 1
		.amdhsa_float_round_mode_32 0
		.amdhsa_float_round_mode_16_64 0
		.amdhsa_float_denorm_mode_32 3
		.amdhsa_float_denorm_mode_16_64 3
		.amdhsa_dx10_clamp 1
		.amdhsa_ieee_mode 1
		.amdhsa_fp16_overflow 0
		.amdhsa_tg_split 0
		.amdhsa_exception_fp_ieee_invalid_op 0
		.amdhsa_exception_fp_denorm_src 0
		.amdhsa_exception_fp_ieee_div_zero 0
		.amdhsa_exception_fp_ieee_overflow 0
		.amdhsa_exception_fp_ieee_underflow 0
		.amdhsa_exception_fp_ieee_inexact 0
		.amdhsa_exception_int_div_zero 0
	.end_amdhsa_kernel

amdhsa.kernels:
  - .agpr_count:     0
    .args:
      - .offset:         0
        .size:           272
        .value_kind:     by_value
      - .offset:         272
        .size:           4
        .value_kind:     hidden_block_count_x
      - .offset:         276
        .size:           4
        .value_kind:     hidden_block_count_y
      - .offset:         280
        .size:           4
        .value_kind:     hidden_block_count_z
      - .offset:         284
        .size:           2
        .value_kind:     hidden_group_size_x
      - .offset:         286
        .size:           2
        .value_kind:     hidden_group_size_y
      - .offset:         288
        .size:           2
        .value_kind:     hidden_group_size_z
      - .offset:         290
        .size:           2
        .value_kind:     hidden_remainder_x
      - .offset:         292
        .size:           2
        .value_kind:     hidden_remainder_y
      - .offset:         294
        .size:           2
        .value_kind:     hidden_remainder_z
      - .offset:         312
        .size:           8
        .value_kind:     hidden_global_offset_x
      - .offset:         320
        .size:           8
        .value_kind:     hidden_global_offset_y
      - .offset:         328
        .size:           8
        .value_kind:     hidden_global_offset_z
      - .offset:         336
        .size:           2
        .value_kind:     hidden_grid_dims
      - .offset:         360
        .size:           8
        .value_kind:     hidden_multigrid_sync_arg
      - .offset:         392
        .size:           4
        .value_kind:     hidden_dynamic_lds_size
    .group_segment_fixed_size: 0
    .kernarg_segment_align: 8
    .kernarg_segment_size: 528
    .language:       OpenCL C
    .language_version:
      - 2
      - 0
    .max_flat_workgroup_size: 512
    .name:           _Z14fwd_megakernel6Params
    .private_segment_fixed_size: 0
    .sgpr_count:     108
    .sgpr_spill_count: 147
    .symbol:         _Z14fwd_megakernel6Params.kd
    .uniform_work_group_size: 1
    .uses_dynamic_stack: false
    .vgpr_count:     256
    .vgpr_spill_count: 0
    .wavefront_size: 64
